# ph_prep key/value path: weight-fragment loads of the K loop hoisted one K-step ahead using two path-private register quads (about 4 instead of 9 exposed L2 round trips per pass), both layers
# speedup vs baseline: 1.0067x; 1.0067x over previous
; __device__ __forceinline__ float bf2f(bf16_t v) { return __uint_as_float(((unsigned)v) << 16); }
; #define LAS __attribute__((address_space(3)))
; __device__ __forceinline__ void ph_prep(bf16_t* Z, const bf16_t* WUQ, const bf16_t* WUKV, const bf16_t* D64, const float* qkq, const float* qkk,
;                                         bf16_t* Q, bf16_t* Kb, bf16_t* Vb, bf16_t* F1lat, bf16_t* F1ctx, unsigned char* lds_) { PH_IDS;
;     ...
;             for (int pass = 0; pass < 2; ++pass) {
;                 f32x4 acc[4][3];
; #pragma unroll
;                 for (int tt = 0; tt < 3; ++tt)
; #pragma unroll
;                     for (int nt = 0; nt < 4; ++nt) acc[nt][tt] = (f32x4){0.f, 0.f, 0.f, 0.f};
; #pragma unroll
;                 for (int ks = 0; ks < 4; ++ks) {
;                     bf16x8 bq[3], aw[4];
; #pragma unroll
;                     for (int tt = 0; tt < 3; ++tt) { bq[tt] = *(const LAS bf16x8*)(sm + O_KV + rl[tt] * P_KV + (32 * ks + 8 * kq) * 2);
;                         if (pass == 0) {
; #pragma unroll
;                             for (int e = 0; e < 8; ++e) { const float f = bf2f((bf16_t)bq[tt][e]); ssq[tt] += f * f; } } }
; #pragma unroll
;                     for (int nt = 0; nt < 4; ++nt) aw[nt] = *(const bf16x8*)(WUKV + (size_t)(h * 128 + pass * 64 + 16 * nt + c16) * 128 + 32 * ks + 8 * kq);
; #pragma unroll
;                     for (int nt = 0; nt < 4; ++nt)
; #pragma unroll
;                         for (int tt = 0; tt < 3; ++tt) acc[nt][tt] = __builtin_amdgcn_mfma_f32_16x16x32_bf16(aw[nt], bq[tt], acc[nt][tt], 0, 0, 0);
;                 }
.LBB0_501:
	v_or_b32_e32 v38, s61, v173
	v_ashrrev_i32_e32 v39, 31, v38
	v_lshlrev_b64 v[22:23], 8, v[38:39]
	v_lshl_add_u64 v[150:151], v[102:103], 0, v[22:23]
	v_or_b32_e32 v22, 16, v38
	v_or_b32_e32 v34, 32, v38
	v_or_b32_e32 v46, 48, v38
	v_ashrrev_i32_e32 v23, 31, v22
	v_ashrrev_i32_e32 v35, 31, v34
	v_ashrrev_i32_e32 v47, 31, v46
	v_lshlrev_b64 v[22:23], 8, v[22:23]
	v_lshlrev_b64 v[34:35], 8, v[34:35]
	v_lshlrev_b64 v[46:47], 8, v[46:47]
	v_lshl_add_u64 v[152:153], v[102:103], 0, v[22:23]
	v_lshl_add_u64 v[154:155], v[102:103], 0, v[34:35]
	v_lshl_add_u64 v[156:157], v[102:103], 0, v[46:47]
	global_load_dwordx4 v[30:33], v[150:151], off
	global_load_dwordx4 v[42:45], v[152:153], off
	global_load_dwordx4 v[54:57], v[154:155], off
	global_load_dwordx4 v[70:73], v[156:157], off
	global_load_dwordx4 v[110:113], v[154:155], off offset:64
	global_load_dwordx4 v[134:137], v[156:157], off offset:64
	ds_read_b128 v[66:69], v86 offset:64
	s_and_b64 vcc, exec, s[18:19]
	s_waitcnt vmcnt(5) lgkmcnt(3)
	v_mfma_f32_16x16x32_bf16 v[22:25], v[30:33], v[18:21], 0
	s_waitcnt lgkmcnt(2)
	v_mfma_f32_16x16x32_bf16 v[26:29], v[30:33], v[58:61], 0
	s_waitcnt lgkmcnt(1)
	v_mfma_f32_16x16x32_bf16 v[30:33], v[30:33], v[62:65], 0
	s_waitcnt vmcnt(4)
	v_mfma_f32_16x16x32_bf16 v[34:37], v[42:45], v[18:21], 0
	v_mfma_f32_16x16x32_bf16 v[38:41], v[42:45], v[58:61], 0
	v_mfma_f32_16x16x32_bf16 v[42:45], v[42:45], v[62:65], 0
	s_waitcnt vmcnt(3)
	v_mfma_f32_16x16x32_bf16 v[46:49], v[54:57], v[18:21], 0
	v_mfma_f32_16x16x32_bf16 v[50:53], v[54:57], v[58:61], 0
	v_mfma_f32_16x16x32_bf16 v[54:57], v[54:57], v[62:65], 0
	s_waitcnt vmcnt(2)
	v_mfma_f32_16x16x32_bf16 v[18:21], v[70:73], v[18:21], 0
	v_mfma_f32_16x16x32_bf16 v[58:61], v[70:73], v[58:61], 0
	v_mfma_f32_16x16x32_bf16 v[62:65], v[70:73], v[62:65], 0
	s_cbranch_vccnz .LBB0_542
	s_waitcnt lgkmcnt(0)
	v_and_b32_e32 v71, 0xffff0000, v66
	v_lshlrev_b32_e32 v70, 16, v66
	v_pk_mul_f32 v[70:71], v[70:71], v[70:71]
	s_nop 0
	v_add_f32_e32 v70, v253, v70
	v_add_f32_e32 v72, v71, v70
	v_and_b32_e32 v71, 0xffff0000, v67
	v_lshlrev_b32_e32 v70, 16, v67
	v_pk_mul_f32 v[70:71], v[70:71], v[70:71]
	s_nop 0
	v_add_f32_e32 v70, v70, v72
	v_add_f32_e32 v72, v71, v70
	v_and_b32_e32 v71, 0xffff0000, v68
	v_lshlrev_b32_e32 v70, 16, v68
	v_pk_mul_f32 v[70:71], v[70:71], v[70:71]
	s_nop 0
	v_add_f32_e32 v70, v70, v72
	v_add_f32_e32 v72, v71, v70
	v_and_b32_e32 v71, 0xffff0000, v69
	v_lshlrev_b32_e32 v70, 16, v69
	v_pk_mul_f32 v[70:71], v[70:71], v[70:71]
	s_nop 0
	v_add_f32_e32 v70, v70, v72
	v_add_f32_e32 v253, v71, v70
	ds_read_b128 v[70:73], v94 offset:64
	s_and_b64 vcc, exec, s[18:19]
	s_cbranch_vccz .LBB0_543

; __device__ __forceinline__ float bf2f(bf16_t v) { return __uint_as_float(((unsigned)v) << 16); }
; #define LAS __attribute__((address_space(3)))
; __device__ __forceinline__ void ph_prep(bf16_t* Z, const bf16_t* WUQ, const bf16_t* WUKV, const bf16_t* D64, const float* qkq, const float* qkk,
;                                         bf16_t* Q, bf16_t* Kb, bf16_t* Vb, bf16_t* F1lat, bf16_t* F1ctx, unsigned char* lds_) { PH_IDS;
;     ...
;                 for (int ks = 0; ks < 4; ++ks) {
;                     bf16x8 bq[3], aw[4];
; #pragma unroll
;                     for (int tt = 0; tt < 3; ++tt) { bq[tt] = *(const LAS bf16x8*)(sm + O_KV + rl[tt] * P_KV + (32 * ks + 8 * kq) * 2);
;                         if (pass == 0) {
; #pragma unroll
;                             for (int e = 0; e < 8; ++e) { const float f = bf2f((bf16_t)bq[tt][e]); ssq[tt] += f * f; } } }
; #pragma unroll
;                     for (int nt = 0; nt < 4; ++nt) aw[nt] = *(const bf16x8*)(WUKV + (size_t)(h * 128 + pass * 64 + 16 * nt + c16) * 128 + 32 * ks + 8 * kq);
; #pragma unroll
;                     for (int nt = 0; nt < 4; ++nt)
; #pragma unroll
;                         for (int tt = 0; tt < 3; ++tt) acc[nt][tt] = __builtin_amdgcn_mfma_f32_16x16x32_bf16(aw[nt], bq[tt], acc[nt][tt], 0, 0, 0);
;                 }
.LBB0_505:
	global_load_dwordx4 v[78:81], v[150:151], off offset:64
	global_load_dwordx4 v[82:85], v[152:153], off offset:64
	s_and_b64 vcc, exec, s[18:19]
	s_waitcnt vmcnt(1) lgkmcnt(2)
	v_mfma_f32_16x16x32_bf16 v[22:25], v[78:81], v[66:69], v[22:25]
	s_waitcnt lgkmcnt(1)
	v_mfma_f32_16x16x32_bf16 v[26:29], v[78:81], v[70:73], v[26:29]
	s_waitcnt lgkmcnt(0)
	v_mfma_f32_16x16x32_bf16 v[30:33], v[78:81], v[74:77], v[30:33]
	s_waitcnt vmcnt(0)
	v_mfma_f32_16x16x32_bf16 v[34:37], v[82:85], v[66:69], v[34:37]
	v_mfma_f32_16x16x32_bf16 v[38:41], v[82:85], v[70:73], v[38:41]
	v_mfma_f32_16x16x32_bf16 v[42:45], v[82:85], v[74:77], v[42:45]
	v_mfma_f32_16x16x32_bf16 v[46:49], v[110:113], v[66:69], v[46:49]
	v_mfma_f32_16x16x32_bf16 v[50:53], v[110:113], v[70:73], v[50:53]
	v_mfma_f32_16x16x32_bf16 v[54:57], v[110:113], v[74:77], v[54:57]
	ds_read_b128 v[78:81], v86 offset:128
	v_mfma_f32_16x16x32_bf16 v[18:21], v[134:137], v[66:69], v[18:21]
	v_mfma_f32_16x16x32_bf16 v[58:61], v[134:137], v[70:73], v[58:61]
	v_mfma_f32_16x16x32_bf16 v[62:65], v[134:137], v[74:77], v[62:65]
	global_load_dwordx4 v[70:73], v[152:153], off offset:128
	global_load_dwordx4 v[74:77], v[154:155], off offset:128
	global_load_dwordx4 v[110:113], v[156:157], off offset:128
	global_load_dwordx4 v[134:137], v[154:155], off offset:192
	s_cbranch_vccnz .LBB0_544
	s_waitcnt lgkmcnt(0)
	v_and_b32_e32 v67, 0xffff0000, v78
	v_lshlrev_b32_e32 v66, 16, v78
	v_pk_mul_f32 v[66:67], v[66:67], v[66:67]
	s_nop 0
	v_add_f32_e32 v66, v253, v66
	v_add_f32_e32 v68, v67, v66
	v_and_b32_e32 v67, 0xffff0000, v79
	v_lshlrev_b32_e32 v66, 16, v79
	v_pk_mul_f32 v[66:67], v[66:67], v[66:67]
	s_nop 0
	v_add_f32_e32 v66, v66, v68
	v_add_f32_e32 v68, v67, v66
	v_and_b32_e32 v67, 0xffff0000, v80
	v_lshlrev_b32_e32 v66, 16, v80
	v_pk_mul_f32 v[66:67], v[66:67], v[66:67]
	s_nop 0
	v_add_f32_e32 v66, v66, v68
	v_add_f32_e32 v68, v67, v66
	v_and_b32_e32 v67, 0xffff0000, v81
	v_lshlrev_b32_e32 v66, 16, v81
	v_pk_mul_f32 v[66:67], v[66:67], v[66:67]
	s_nop 0
	v_add_f32_e32 v66, v66, v68
	v_add_f32_e32 v253, v67, v66
	ds_read_b128 v[82:85], v94 offset:128
	s_and_b64 vcc, exec, s[18:19]
	s_cbranch_vccz .LBB0_545

; __device__ __forceinline__ float bf2f(bf16_t v) { return __uint_as_float(((unsigned)v) << 16); }
; #define LAS __attribute__((address_space(3)))
; __device__ __forceinline__ void ph_prep(bf16_t* Z, const bf16_t* WUQ, const bf16_t* WUKV, const bf16_t* D64, const float* qkq, const float* qkk,
;                                         bf16_t* Q, bf16_t* Kb, bf16_t* Vb, bf16_t* F1lat, bf16_t* F1ctx, unsigned char* lds_) { PH_IDS;
;     ...
;                 for (int ks = 0; ks < 4; ++ks) {
;                     bf16x8 bq[3], aw[4];
; #pragma unroll
;                     for (int tt = 0; tt < 3; ++tt) { bq[tt] = *(const LAS bf16x8*)(sm + O_KV + rl[tt] * P_KV + (32 * ks + 8 * kq) * 2);
;                         if (pass == 0) {
; #pragma unroll
;                             for (int e = 0; e < 8; ++e) { const float f = bf2f((bf16_t)bq[tt][e]); ssq[tt] += f * f; } } }
; #pragma unroll
;                     for (int nt = 0; nt < 4; ++nt) aw[nt] = *(const bf16x8*)(WUKV + (size_t)(h * 128 + pass * 64 + 16 * nt + c16) * 128 + 32 * ks + 8 * kq);
; #pragma unroll
;                     for (int nt = 0; nt < 4; ++nt)
; #pragma unroll
;                         for (int tt = 0; tt < 3; ++tt) acc[nt][tt] = __builtin_amdgcn_mfma_f32_16x16x32_bf16(aw[nt], bq[tt], acc[nt][tt], 0, 0, 0);
;                 }
.LBB0_509:
	global_load_dwordx4 v[66:69], v[150:151], off offset:128
	ds_read_b128 v[86:89], v86 offset:192
	s_and_b64 vcc, exec, s[18:19]
	s_waitcnt vmcnt(0) lgkmcnt(3)
	v_mfma_f32_16x16x32_bf16 v[22:25], v[66:69], v[78:81], v[22:25]
	s_waitcnt lgkmcnt(2)
	v_mfma_f32_16x16x32_bf16 v[26:29], v[66:69], v[82:85], v[26:29]
	s_waitcnt lgkmcnt(1)
	v_mfma_f32_16x16x32_bf16 v[30:33], v[66:69], v[90:93], v[30:33]
	v_mfma_f32_16x16x32_bf16 v[66:69], v[70:73], v[90:93], v[42:45]
	s_nop 2
	v_mfma_f32_16x16x32_bf16 v[34:37], v[70:73], v[78:81], v[34:37]
	v_mfma_f32_16x16x32_bf16 v[38:41], v[70:73], v[82:85], v[38:41]
	v_mfma_f32_16x16x32_bf16 v[70:73], v[74:77], v[78:81], v[46:49]
	v_mfma_f32_16x16x32_bf16 v[50:53], v[74:77], v[82:85], v[50:53]
	v_mfma_f32_16x16x32_bf16 v[74:77], v[74:77], v[90:93], v[54:57]
	v_mfma_f32_16x16x32_bf16 v[18:21], v[110:113], v[78:81], v[18:21]
	v_mfma_f32_16x16x32_bf16 v[78:81], v[110:113], v[82:85], v[58:61]
	v_mfma_f32_16x16x32_bf16 v[82:85], v[110:113], v[90:93], v[62:65]
	global_load_dwordx4 v[54:57], v[152:153], off offset:192
	global_load_dwordx4 v[110:113], v[156:157], off offset:192
	s_cbranch_vccnz .LBB0_546
	s_waitcnt lgkmcnt(0)
	v_and_b32_e32 v43, 0xffff0000, v86
	v_lshlrev_b32_e32 v42, 16, v86
	v_pk_mul_f32 v[42:43], v[42:43], v[42:43]
	s_nop 0
	v_add_f32_e32 v42, v253, v42
	v_add_f32_e32 v44, v43, v42
	v_and_b32_e32 v43, 0xffff0000, v87
	v_lshlrev_b32_e32 v42, 16, v87
	v_pk_mul_f32 v[42:43], v[42:43], v[42:43]
	s_nop 0
	v_add_f32_e32 v42, v42, v44
	v_add_f32_e32 v44, v43, v42
	v_and_b32_e32 v43, 0xffff0000, v88
	v_lshlrev_b32_e32 v42, 16, v88
	v_pk_mul_f32 v[42:43], v[42:43], v[42:43]
	s_nop 0
	v_add_f32_e32 v42, v42, v44
	v_add_f32_e32 v44, v43, v42
	v_and_b32_e32 v43, 0xffff0000, v89
	v_lshlrev_b32_e32 v42, 16, v89
	v_pk_mul_f32 v[42:43], v[42:43], v[42:43]
	s_nop 0
	v_add_f32_e32 v42, v42, v44
	v_add_f32_e32 v253, v43, v42
	ds_read_b128 v[90:93], v94 offset:192
	s_and_b64 vcc, exec, s[18:19]
	s_cbranch_vccz .LBB0_547

; __device__ __forceinline__ float bf2f(bf16_t v) { return __uint_as_float(((unsigned)v) << 16); }
; #define LAS __attribute__((address_space(3)))
; __device__ __forceinline__ unsigned pk2(float lo, float hi) { unsigned r; asm volatile("v_cvt_pk_bf16_f32 %0, %1, %2" : "=v"(r) : "v"(lo), "v"(hi)); return r; }
; __device__ __forceinline__ void ph_prep(bf16_t* Z, const bf16_t* WUQ, const bf16_t* WUKV, const bf16_t* D64, const float* qkq, const float* qkk,
;                                         bf16_t* Q, bf16_t* Kb, bf16_t* Vb, bf16_t* F1lat, bf16_t* F1ctx, unsigned char* lds_) { PH_IDS;
;     ...
;                 for (int ks = 0; ks < 4; ++ks) {
;                     bf16x8 bq[3], aw[4];
; #pragma unroll
;                     for (int tt = 0; tt < 3; ++tt) { bq[tt] = *(const LAS bf16x8*)(sm + O_KV + rl[tt] * P_KV + (32 * ks + 8 * kq) * 2);
;                         if (pass == 0) {
; #pragma unroll
;                             for (int e = 0; e < 8; ++e) { const float f = bf2f((bf16_t)bq[tt][e]); ssq[tt] += f * f; } } }
; #pragma unroll
;                     for (int nt = 0; nt < 4; ++nt) aw[nt] = *(const bf16x8*)(WUKV + (size_t)(h * 128 + pass * 64 + 16 * nt + c16) * 128 + 32 * ks + 8 * kq);
; #pragma unroll
;                     for (int nt = 0; nt < 4; ++nt)
; #pragma unroll
;                         for (int tt = 0; tt < 3; ++tt) acc[nt][tt] = __builtin_amdgcn_mfma_f32_16x16x32_bf16(aw[nt], bq[tt], acc[nt][tt], 0, 0, 0);
;                 }
;     ...
;                         bf16_t* vo = Vb + ((size_t)(b * 4 + h) * 2304 + ki) * 64 + 4 * kq;
; #pragma unroll
;                         for (int nt = 0; nt < 4; ++nt) { fa::u32x2 o; o.x = fa::pk2(acc[nt][tt][0] * rstd[tt], acc[nt][tt][1] * rstd[tt]); o.y = fa::pk2(acc[nt][tt][2] * rstd[tt], acc[nt][tt][3] * rstd[tt]);
;                             if (valid[tt]) *(fa::u32x2*)(vo + 16 * nt) = o; }
.LBB0_513:
	global_load_dwordx4 v[42:45], v[150:151], off offset:192
	s_mov_b64 s[18:19], -1
	s_and_b64 vcc, exec, s[34:35]
	s_waitcnt vmcnt(0) lgkmcnt(2)
	v_mfma_f32_16x16x32_bf16 v[62:65], v[42:45], v[86:89], v[22:25]
	s_nop 2
	s_waitcnt lgkmcnt(1)
	v_mfma_f32_16x16x32_bf16 v[46:49], v[42:45], v[90:93], v[26:29]
	s_waitcnt lgkmcnt(0)
	v_mfma_f32_16x16x32_bf16 v[26:29], v[54:57], v[94:97], v[66:69]
	s_nop 2
	v_mfma_f32_16x16x32_bf16 v[30:33], v[42:45], v[94:97], v[30:33]
	v_mfma_f32_16x16x32_bf16 v[58:61], v[54:57], v[86:89], v[34:37]
	v_mfma_f32_16x16x32_bf16 v[42:45], v[54:57], v[90:93], v[38:41]
	v_mfma_f32_16x16x32_bf16 v[54:57], v[134:137], v[86:89], v[70:73]
	v_mfma_f32_16x16x32_bf16 v[38:41], v[134:137], v[90:93], v[50:53]
	v_mfma_f32_16x16x32_bf16 v[22:25], v[134:137], v[94:97], v[74:77]
	v_mfma_f32_16x16x32_bf16 v[50:53], v[110:113], v[86:89], v[18:21]
	v_mfma_f32_16x16x32_bf16 v[34:37], v[110:113], v[90:93], v[78:81]
	v_mfma_f32_16x16x32_bf16 v[18:21], v[110:113], v[94:97], v[82:85]
	s_cbranch_vccz .LBB0_515
	v_mul_f32_e32 v66, v195, v62
	v_mul_f32_e32 v67, v195, v63
	v_cvt_pk_bf16_f32 v66, v66, v67
	v_mul_f32_e32 v67, v195, v64
	v_mul_f32_e32 v68, v195, v65
	v_cvt_pk_bf16_f32 v67, v67, v68
	global_store_dwordx2 v[138:139], v[66:67], off
	v_mul_f32_e32 v66, v195, v58
	v_mul_f32_e32 v67, v195, v59
	v_cvt_pk_bf16_f32 v66, v66, v67
	v_mul_f32_e32 v67, v195, v60
	v_mul_f32_e32 v68, v195, v61
	v_cvt_pk_bf16_f32 v67, v67, v68
	global_store_dwordx2 v[138:139], v[66:67], off offset:32
	v_mul_f32_e32 v66, v195, v54
	v_mul_f32_e32 v67, v195, v55
	v_cvt_pk_bf16_f32 v66, v66, v67
	v_mul_f32_e32 v67, v195, v56
	v_mul_f32_e32 v68, v195, v57
	v_cvt_pk_bf16_f32 v67, v67, v68
	global_store_dwordx2 v[138:139], v[66:67], off offset:64
	v_mul_f32_e32 v66, v195, v50
	v_mul_f32_e32 v67, v195, v51
	v_cvt_pk_bf16_f32 v66, v66, v67
	v_mul_f32_e32 v67, v195, v52
	v_mul_f32_e32 v68, v195, v53
	v_cvt_pk_bf16_f32 v67, v67, v68
	global_store_dwordx2 v[138:139], v[66:67], off offset:96
	s_mov_b64 s[18:19], 0

; __device__ __forceinline__ float bf2f(bf16_t v) { return __uint_as_float(((unsigned)v) << 16); }
; #define LAS __attribute__((address_space(3)))
; __device__ __forceinline__ void ph_prep(bf16_t* Z, const bf16_t* WUQ, const bf16_t* WUKV, const bf16_t* D64, const float* qkq, const float* qkk,
;                                         bf16_t* Q, bf16_t* Kb, bf16_t* Vb, bf16_t* F1lat, bf16_t* F1ctx, unsigned char* lds_) { PH_IDS;
;     ...
;             for (int pass = 0; pass < 2; ++pass) {
;                 f32x4 acc[4][3];
; #pragma unroll
;                 for (int tt = 0; tt < 3; ++tt)
; #pragma unroll
;                     for (int nt = 0; nt < 4; ++nt) acc[nt][tt] = (f32x4){0.f, 0.f, 0.f, 0.f};
; #pragma unroll
;                 for (int ks = 0; ks < 4; ++ks) {
;                     bf16x8 bq[3], aw[4];
; #pragma unroll
;                     for (int tt = 0; tt < 3; ++tt) { bq[tt] = *(const LAS bf16x8*)(sm + O_KV + rl[tt] * P_KV + (32 * ks + 8 * kq) * 2);
;                         if (pass == 0) {
; #pragma unroll
;                             for (int e = 0; e < 8; ++e) { const float f = bf2f((bf16_t)bq[tt][e]); ssq[tt] += f * f; } } }
; #pragma unroll
;                     for (int nt = 0; nt < 4; ++nt) aw[nt] = *(const bf16x8*)(WUKV + (size_t)(h * 128 + pass * 64 + 16 * nt + c16) * 128 + 32 * ks + 8 * kq);
; #pragma unroll
;                     for (int nt = 0; nt < 4; ++nt)
; #pragma unroll
;                         for (int tt = 0; tt < 3; ++tt) acc[nt][tt] = __builtin_amdgcn_mfma_f32_16x16x32_bf16(aw[nt], bq[tt], acc[nt][tt], 0, 0, 0);
;                 }
.LBB0_2337:
	v_or_b32_e32 v38, s61, v173
	v_ashrrev_i32_e32 v39, 31, v38
	v_lshlrev_b64 v[22:23], 8, v[38:39]
	v_lshl_add_u64 v[150:151], v[102:103], 0, v[22:23]
	v_or_b32_e32 v22, 16, v38
	v_or_b32_e32 v34, 32, v38
	v_or_b32_e32 v46, 48, v38
	v_ashrrev_i32_e32 v23, 31, v22
	v_ashrrev_i32_e32 v35, 31, v34
	v_ashrrev_i32_e32 v47, 31, v46
	v_lshlrev_b64 v[22:23], 8, v[22:23]
	v_lshlrev_b64 v[34:35], 8, v[34:35]
	v_lshlrev_b64 v[46:47], 8, v[46:47]
	v_lshl_add_u64 v[152:153], v[102:103], 0, v[22:23]
	v_lshl_add_u64 v[154:155], v[102:103], 0, v[34:35]
	v_lshl_add_u64 v[156:157], v[102:103], 0, v[46:47]
	global_load_dwordx4 v[30:33], v[150:151], off
	global_load_dwordx4 v[42:45], v[152:153], off
	global_load_dwordx4 v[54:57], v[154:155], off
	global_load_dwordx4 v[70:73], v[156:157], off
	global_load_dwordx4 v[110:113], v[154:155], off offset:64
	global_load_dwordx4 v[134:137], v[156:157], off offset:64
	ds_read_b128 v[66:69], v86 offset:64
	s_and_b64 vcc, exec, s[18:19]
	s_waitcnt vmcnt(5) lgkmcnt(3)
	v_mfma_f32_16x16x32_bf16 v[22:25], v[30:33], v[18:21], 0
	s_waitcnt lgkmcnt(2)
	v_mfma_f32_16x16x32_bf16 v[26:29], v[30:33], v[58:61], 0
	s_waitcnt lgkmcnt(1)
	v_mfma_f32_16x16x32_bf16 v[30:33], v[30:33], v[62:65], 0
	s_waitcnt vmcnt(4)
	v_mfma_f32_16x16x32_bf16 v[34:37], v[42:45], v[18:21], 0
	v_mfma_f32_16x16x32_bf16 v[38:41], v[42:45], v[58:61], 0
	v_mfma_f32_16x16x32_bf16 v[42:45], v[42:45], v[62:65], 0
	s_waitcnt vmcnt(3)
	v_mfma_f32_16x16x32_bf16 v[46:49], v[54:57], v[18:21], 0
	v_mfma_f32_16x16x32_bf16 v[50:53], v[54:57], v[58:61], 0
	v_mfma_f32_16x16x32_bf16 v[54:57], v[54:57], v[62:65], 0
	s_waitcnt vmcnt(2)
	v_mfma_f32_16x16x32_bf16 v[18:21], v[70:73], v[18:21], 0
	v_mfma_f32_16x16x32_bf16 v[58:61], v[70:73], v[58:61], 0
	v_mfma_f32_16x16x32_bf16 v[62:65], v[70:73], v[62:65], 0
	s_cbranch_vccnz .LBB0_2378
	s_waitcnt lgkmcnt(0)
	v_and_b32_e32 v71, 0xffff0000, v66
	v_lshlrev_b32_e32 v70, 16, v66
	v_pk_mul_f32 v[70:71], v[70:71], v[70:71]
	s_nop 0
	v_add_f32_e32 v70, v252, v70
	v_add_f32_e32 v72, v71, v70
	v_and_b32_e32 v71, 0xffff0000, v67
	v_lshlrev_b32_e32 v70, 16, v67
	v_pk_mul_f32 v[70:71], v[70:71], v[70:71]
	s_nop 0
	v_add_f32_e32 v70, v70, v72
	v_add_f32_e32 v72, v71, v70
	v_and_b32_e32 v71, 0xffff0000, v68
	v_lshlrev_b32_e32 v70, 16, v68
	v_pk_mul_f32 v[70:71], v[70:71], v[70:71]
	s_nop 0
	v_add_f32_e32 v70, v70, v72
	v_add_f32_e32 v72, v71, v70
	v_and_b32_e32 v71, 0xffff0000, v69
	v_lshlrev_b32_e32 v70, 16, v69
	v_pk_mul_f32 v[70:71], v[70:71], v[70:71]
	s_nop 0
	v_add_f32_e32 v70, v70, v72
	v_add_f32_e32 v252, v71, v70
	ds_read_b128 v[70:73], v94 offset:64
	s_and_b64 vcc, exec, s[18:19]
	s_cbranch_vccz .LBB0_2379

; __device__ __forceinline__ float bf2f(bf16_t v) { return __uint_as_float(((unsigned)v) << 16); }
; #define LAS __attribute__((address_space(3)))
; __device__ __forceinline__ void ph_prep(bf16_t* Z, const bf16_t* WUQ, const bf16_t* WUKV, const bf16_t* D64, const float* qkq, const float* qkk,
;                                         bf16_t* Q, bf16_t* Kb, bf16_t* Vb, bf16_t* F1lat, bf16_t* F1ctx, unsigned char* lds_) { PH_IDS;
;     ...
;                 for (int ks = 0; ks < 4; ++ks) {
;                     bf16x8 bq[3], aw[4];
; #pragma unroll
;                     for (int tt = 0; tt < 3; ++tt) { bq[tt] = *(const LAS bf16x8*)(sm + O_KV + rl[tt] * P_KV + (32 * ks + 8 * kq) * 2);
;                         if (pass == 0) {
; #pragma unroll
;                             for (int e = 0; e < 8; ++e) { const float f = bf2f((bf16_t)bq[tt][e]); ssq[tt] += f * f; } } }
; #pragma unroll
;                     for (int nt = 0; nt < 4; ++nt) aw[nt] = *(const bf16x8*)(WUKV + (size_t)(h * 128 + pass * 64 + 16 * nt + c16) * 128 + 32 * ks + 8 * kq);
; #pragma unroll
;                     for (int nt = 0; nt < 4; ++nt)
; #pragma unroll
;                         for (int tt = 0; tt < 3; ++tt) acc[nt][tt] = __builtin_amdgcn_mfma_f32_16x16x32_bf16(aw[nt], bq[tt], acc[nt][tt], 0, 0, 0);
;                 }
.LBB0_2341:
	global_load_dwordx4 v[78:81], v[150:151], off offset:64
	global_load_dwordx4 v[82:85], v[152:153], off offset:64
	s_and_b64 vcc, exec, s[18:19]
	s_waitcnt vmcnt(1) lgkmcnt(2)
	v_mfma_f32_16x16x32_bf16 v[22:25], v[78:81], v[66:69], v[22:25]
	s_waitcnt lgkmcnt(1)
	v_mfma_f32_16x16x32_bf16 v[26:29], v[78:81], v[70:73], v[26:29]
	s_waitcnt lgkmcnt(0)
	v_mfma_f32_16x16x32_bf16 v[30:33], v[78:81], v[74:77], v[30:33]
	s_waitcnt vmcnt(0)
	v_mfma_f32_16x16x32_bf16 v[34:37], v[82:85], v[66:69], v[34:37]
	v_mfma_f32_16x16x32_bf16 v[38:41], v[82:85], v[70:73], v[38:41]
	v_mfma_f32_16x16x32_bf16 v[42:45], v[82:85], v[74:77], v[42:45]
	v_mfma_f32_16x16x32_bf16 v[46:49], v[110:113], v[66:69], v[46:49]
	v_mfma_f32_16x16x32_bf16 v[50:53], v[110:113], v[70:73], v[50:53]
	v_mfma_f32_16x16x32_bf16 v[54:57], v[110:113], v[74:77], v[54:57]
	ds_read_b128 v[78:81], v86 offset:128
	v_mfma_f32_16x16x32_bf16 v[18:21], v[134:137], v[66:69], v[18:21]
	v_mfma_f32_16x16x32_bf16 v[58:61], v[134:137], v[70:73], v[58:61]
	v_mfma_f32_16x16x32_bf16 v[62:65], v[134:137], v[74:77], v[62:65]
	global_load_dwordx4 v[70:73], v[152:153], off offset:128
	global_load_dwordx4 v[74:77], v[154:155], off offset:128
	global_load_dwordx4 v[110:113], v[156:157], off offset:128
	global_load_dwordx4 v[134:137], v[154:155], off offset:192
	s_cbranch_vccnz .LBB0_2380
	s_waitcnt lgkmcnt(0)
	v_and_b32_e32 v67, 0xffff0000, v78
	v_lshlrev_b32_e32 v66, 16, v78
	v_pk_mul_f32 v[66:67], v[66:67], v[66:67]
	s_nop 0
	v_add_f32_e32 v66, v252, v66
	v_add_f32_e32 v68, v67, v66
	v_and_b32_e32 v67, 0xffff0000, v79
	v_lshlrev_b32_e32 v66, 16, v79
	v_pk_mul_f32 v[66:67], v[66:67], v[66:67]
	s_nop 0
	v_add_f32_e32 v66, v66, v68
	v_add_f32_e32 v68, v67, v66
	v_and_b32_e32 v67, 0xffff0000, v80
	v_lshlrev_b32_e32 v66, 16, v80
	v_pk_mul_f32 v[66:67], v[66:67], v[66:67]
	s_nop 0
	v_add_f32_e32 v66, v66, v68
	v_add_f32_e32 v68, v67, v66
	v_and_b32_e32 v67, 0xffff0000, v81
	v_lshlrev_b32_e32 v66, 16, v81
	v_pk_mul_f32 v[66:67], v[66:67], v[66:67]
	s_nop 0
	v_add_f32_e32 v66, v66, v68
	v_add_f32_e32 v252, v67, v66
	ds_read_b128 v[82:85], v94 offset:128
	s_and_b64 vcc, exec, s[18:19]
	s_cbranch_vccz .LBB0_2381

; __device__ __forceinline__ float bf2f(bf16_t v) { return __uint_as_float(((unsigned)v) << 16); }
; #define LAS __attribute__((address_space(3)))
; __device__ __forceinline__ void ph_prep(bf16_t* Z, const bf16_t* WUQ, const bf16_t* WUKV, const bf16_t* D64, const float* qkq, const float* qkk,
;                                         bf16_t* Q, bf16_t* Kb, bf16_t* Vb, bf16_t* F1lat, bf16_t* F1ctx, unsigned char* lds_) { PH_IDS;
;     ...
;                 for (int ks = 0; ks < 4; ++ks) {
;                     bf16x8 bq[3], aw[4];
; #pragma unroll
;                     for (int tt = 0; tt < 3; ++tt) { bq[tt] = *(const LAS bf16x8*)(sm + O_KV + rl[tt] * P_KV + (32 * ks + 8 * kq) * 2);
;                         if (pass == 0) {
; #pragma unroll
;                             for (int e = 0; e < 8; ++e) { const float f = bf2f((bf16_t)bq[tt][e]); ssq[tt] += f * f; } } }
; #pragma unroll
;                     for (int nt = 0; nt < 4; ++nt) aw[nt] = *(const bf16x8*)(WUKV + (size_t)(h * 128 + pass * 64 + 16 * nt + c16) * 128 + 32 * ks + 8 * kq);
; #pragma unroll
;                     for (int nt = 0; nt < 4; ++nt)
; #pragma unroll
;                         for (int tt = 0; tt < 3; ++tt) acc[nt][tt] = __builtin_amdgcn_mfma_f32_16x16x32_bf16(aw[nt], bq[tt], acc[nt][tt], 0, 0, 0);
;                 }
.LBB0_2345:
	global_load_dwordx4 v[66:69], v[150:151], off offset:128
	ds_read_b128 v[86:89], v86 offset:192
	s_and_b64 vcc, exec, s[18:19]
	s_waitcnt vmcnt(0) lgkmcnt(3)
	v_mfma_f32_16x16x32_bf16 v[22:25], v[66:69], v[78:81], v[22:25]
	s_waitcnt lgkmcnt(2)
	v_mfma_f32_16x16x32_bf16 v[26:29], v[66:69], v[82:85], v[26:29]
	s_waitcnt lgkmcnt(1)
	v_mfma_f32_16x16x32_bf16 v[30:33], v[66:69], v[90:93], v[30:33]
	v_mfma_f32_16x16x32_bf16 v[66:69], v[70:73], v[90:93], v[42:45]
	s_nop 2
	v_mfma_f32_16x16x32_bf16 v[34:37], v[70:73], v[78:81], v[34:37]
	v_mfma_f32_16x16x32_bf16 v[38:41], v[70:73], v[82:85], v[38:41]
	v_mfma_f32_16x16x32_bf16 v[70:73], v[74:77], v[78:81], v[46:49]
	v_mfma_f32_16x16x32_bf16 v[50:53], v[74:77], v[82:85], v[50:53]
	v_mfma_f32_16x16x32_bf16 v[74:77], v[74:77], v[90:93], v[54:57]
	v_mfma_f32_16x16x32_bf16 v[18:21], v[110:113], v[78:81], v[18:21]
	v_mfma_f32_16x16x32_bf16 v[78:81], v[110:113], v[82:85], v[58:61]
	v_mfma_f32_16x16x32_bf16 v[82:85], v[110:113], v[90:93], v[62:65]
	global_load_dwordx4 v[54:57], v[152:153], off offset:192
	global_load_dwordx4 v[110:113], v[156:157], off offset:192
	s_cbranch_vccnz .LBB0_2382
	s_waitcnt lgkmcnt(0)
	v_and_b32_e32 v43, 0xffff0000, v86
	v_lshlrev_b32_e32 v42, 16, v86
	v_pk_mul_f32 v[42:43], v[42:43], v[42:43]
	s_nop 0
	v_add_f32_e32 v42, v252, v42
	v_add_f32_e32 v44, v43, v42
	v_and_b32_e32 v43, 0xffff0000, v87
	v_lshlrev_b32_e32 v42, 16, v87
	v_pk_mul_f32 v[42:43], v[42:43], v[42:43]
	s_nop 0
	v_add_f32_e32 v42, v42, v44
	v_add_f32_e32 v44, v43, v42
	v_and_b32_e32 v43, 0xffff0000, v88
	v_lshlrev_b32_e32 v42, 16, v88
	v_pk_mul_f32 v[42:43], v[42:43], v[42:43]
	s_nop 0
	v_add_f32_e32 v42, v42, v44
	v_add_f32_e32 v44, v43, v42
	v_and_b32_e32 v43, 0xffff0000, v89
	v_lshlrev_b32_e32 v42, 16, v89
	v_pk_mul_f32 v[42:43], v[42:43], v[42:43]
	s_nop 0
	v_add_f32_e32 v42, v42, v44
	v_add_f32_e32 v252, v43, v42
	ds_read_b128 v[90:93], v94 offset:192
	s_and_b64 vcc, exec, s[18:19]
	s_cbranch_vccz .LBB0_2383

; __device__ __forceinline__ float bf2f(bf16_t v) { return __uint_as_float(((unsigned)v) << 16); }
; #define LAS __attribute__((address_space(3)))
; __device__ __forceinline__ unsigned pk2(float lo, float hi) { unsigned r; asm volatile("v_cvt_pk_bf16_f32 %0, %1, %2" : "=v"(r) : "v"(lo), "v"(hi)); return r; }
; __device__ __forceinline__ void ph_prep(bf16_t* Z, const bf16_t* WUQ, const bf16_t* WUKV, const bf16_t* D64, const float* qkq, const float* qkk,
;                                         bf16_t* Q, bf16_t* Kb, bf16_t* Vb, bf16_t* F1lat, bf16_t* F1ctx, unsigned char* lds_) { PH_IDS;
;     ...
;                 for (int ks = 0; ks < 4; ++ks) {
;                     bf16x8 bq[3], aw[4];
; #pragma unroll
;                     for (int tt = 0; tt < 3; ++tt) { bq[tt] = *(const LAS bf16x8*)(sm + O_KV + rl[tt] * P_KV + (32 * ks + 8 * kq) * 2);
;                         if (pass == 0) {
; #pragma unroll
;                             for (int e = 0; e < 8; ++e) { const float f = bf2f((bf16_t)bq[tt][e]); ssq[tt] += f * f; } } }
; #pragma unroll
;                     for (int nt = 0; nt < 4; ++nt) aw[nt] = *(const bf16x8*)(WUKV + (size_t)(h * 128 + pass * 64 + 16 * nt + c16) * 128 + 32 * ks + 8 * kq);
; #pragma unroll
;                     for (int nt = 0; nt < 4; ++nt)
; #pragma unroll
;                         for (int tt = 0; tt < 3; ++tt) acc[nt][tt] = __builtin_amdgcn_mfma_f32_16x16x32_bf16(aw[nt], bq[tt], acc[nt][tt], 0, 0, 0);
;                 }
;     ...
;                         bf16_t* vo = Vb + ((size_t)(b * 4 + h) * 2304 + ki) * 64 + 4 * kq;
; #pragma unroll
;                         for (int nt = 0; nt < 4; ++nt) { fa::u32x2 o; o.x = fa::pk2(acc[nt][tt][0] * rstd[tt], acc[nt][tt][1] * rstd[tt]); o.y = fa::pk2(acc[nt][tt][2] * rstd[tt], acc[nt][tt][3] * rstd[tt]);
;                             if (valid[tt]) *(fa::u32x2*)(vo + 16 * nt) = o; }
.LBB0_2349:
	global_load_dwordx4 v[42:45], v[150:151], off offset:192
	s_mov_b64 s[18:19], -1
	s_and_b64 vcc, exec, s[34:35]
	s_waitcnt vmcnt(0) lgkmcnt(2)
	v_mfma_f32_16x16x32_bf16 v[62:65], v[42:45], v[86:89], v[22:25]
	s_nop 2
	s_waitcnt lgkmcnt(1)
	v_mfma_f32_16x16x32_bf16 v[46:49], v[42:45], v[90:93], v[26:29]
	s_waitcnt lgkmcnt(0)
	v_mfma_f32_16x16x32_bf16 v[26:29], v[54:57], v[94:97], v[66:69]
	s_nop 2
	v_mfma_f32_16x16x32_bf16 v[30:33], v[42:45], v[94:97], v[30:33]
	v_mfma_f32_16x16x32_bf16 v[58:61], v[54:57], v[86:89], v[34:37]
	v_mfma_f32_16x16x32_bf16 v[42:45], v[54:57], v[90:93], v[38:41]
	v_mfma_f32_16x16x32_bf16 v[54:57], v[134:137], v[86:89], v[70:73]
	v_mfma_f32_16x16x32_bf16 v[38:41], v[134:137], v[90:93], v[50:53]
	v_mfma_f32_16x16x32_bf16 v[22:25], v[134:137], v[94:97], v[74:77]
	v_mfma_f32_16x16x32_bf16 v[50:53], v[110:113], v[86:89], v[18:21]
	v_mfma_f32_16x16x32_bf16 v[34:37], v[110:113], v[90:93], v[78:81]
	v_mfma_f32_16x16x32_bf16 v[18:21], v[110:113], v[94:97], v[82:85]
	s_cbranch_vccz .LBB0_2351
	v_mul_f32_e32 v66, v194, v62
	v_mul_f32_e32 v67, v194, v63
	v_cvt_pk_bf16_f32 v66, v66, v67
	v_mul_f32_e32 v67, v194, v64
	v_mul_f32_e32 v68, v194, v65
	v_cvt_pk_bf16_f32 v67, v67, v68
	global_store_dwordx2 v[138:139], v[66:67], off
	v_mul_f32_e32 v66, v194, v58
	v_mul_f32_e32 v67, v194, v59
	v_cvt_pk_bf16_f32 v66, v66, v67
	v_mul_f32_e32 v67, v194, v60
	v_mul_f32_e32 v68, v194, v61
	v_cvt_pk_bf16_f32 v67, v67, v68
	global_store_dwordx2 v[138:139], v[66:67], off offset:32
	v_mul_f32_e32 v66, v194, v54
	v_mul_f32_e32 v67, v194, v55
	v_cvt_pk_bf16_f32 v66, v66, v67
	v_mul_f32_e32 v67, v194, v56
	v_mul_f32_e32 v68, v194, v57
	v_cvt_pk_bf16_f32 v67, v67, v68
	global_store_dwordx2 v[138:139], v[66:67], off offset:64
	v_mul_f32_e32 v66, v194, v50
	v_mul_f32_e32 v67, v194, v51
	v_cvt_pk_bf16_f32 v66, v66, v67
	v_mul_f32_e32 v67, v194, v52
	v_mul_f32_e32 v68, v194, v53
	v_cvt_pk_bf16_f32 v67, v67, v68
	global_store_dwordx2 v[138:139], v[66:67], off offset:96
	s_mov_b64 s[18:19], 0
